# grid barrier: top arrival count replicated per XCD (each XCD polls its own copy; the XCD-last arriver posts to all copies)
# speedup vs baseline: 1.0132x; 1.0132x over previous
.LBB0_94:
	s_waitcnt lgkmcnt(0)
	s_mov_b32 s2, s91
	s_mov_b32 s4, 0
	s_waitcnt vmcnt(0)
	s_mov_b32 s5, 0
	v_or_b32_e32 v0, s2, v230
	v_cmp_eq_u32_e32 vcc, 0, v0
	s_barrier
	s_and_saveexec_b64 s[2:3], vcc
	s_cbranch_execz .LBB0_138
	v_writelane_b32 v2, s4, 1
	v_writelane_b32 v2, s5, 2
	v_writelane_b32 v2, s6, 3
	v_writelane_b32 v2, s7, 4
	v_readlane_b32 s4, v251, 0
	v_readlane_b32 s5, v251, 1
	s_getreg_b32 s6, hwreg(HW_REG_XCC_ID, 0, 4)
	s_load_dword s7, s[4:5], 0x100
	s_load_dwordx2 s[4:5], s[4:5], 0xf0
	v_mov_b32_e32 v0, 0x20010
	ds_read_b32 v3, v0
	ds_read_b32 v4, v0 offset:4
	ds_read_b32 v5, v0 offset:8
	s_and_b32 s6, s6, 15
	s_lshl_b32 s6, s6, 8
	v_mov_b32_e32 v8, 1
	v_mov_b32_e32 v14, 0
	s_waitcnt lgkmcnt(0)
	s_add_u32 s4, s4, 0xee42000
	s_addc_u32 s5, s5, 0
	v_mov_b32_e32 v6, s6
	v_add_u32_e32 v7, 0x400, v6
	v_add_u32_e32 v6, 0x1400, v6
	v_add_u32_e32 v13, 0x1000, v6
	v_cmp_ne_u32_e32 vcc, 0, v3
	s_cbranch_vccnz .Lhb_have_1
	v_mov_b32_e32 v15, 0x400

.Lhb_have_1:
	buffer_inv sc1
	global_atomic_add v9, v6, v8, s[4:5] sc0
	v_add_u32_e32 v10, 1, v5
	v_mul_lo_u32 v11, v10, v3
	v_mul_lo_u32 v12, v10, v4
	s_waitcnt vmcnt(0)
	v_add_u32_e32 v9, 1, v9
	v_cmp_eq_u32_e32 vcc, v9, v11
	s_cbranch_vccz .Lhb_poll_1
	buffer_wbl2 sc1
	s_waitcnt vmcnt(0)
	v_mov_b32_e32 v7, 0x2400
	global_atomic_add v7, v8, s[4:5]
	v_add_u32_e32 v7, 0x100, v7
	global_atomic_add v7, v8, s[4:5]
	v_add_u32_e32 v7, 0x100, v7
	global_atomic_add v7, v8, s[4:5]
	v_add_u32_e32 v7, 0x100, v7
	global_atomic_add v7, v8, s[4:5]
	v_add_u32_e32 v7, 0x100, v7
	global_atomic_add v7, v8, s[4:5]
	v_add_u32_e32 v7, 0x100, v7
	global_atomic_add v7, v8, s[4:5]
	v_add_u32_e32 v7, 0x100, v7
	global_atomic_add v7, v8, s[4:5]
	v_add_u32_e32 v7, 0x100, v7
	global_atomic_add v7, v8, s[4:5]
	v_add_u32_e32 v7, 0x100, v7
	global_atomic_add v7, v8, s[4:5]
	v_add_u32_e32 v7, 0x100, v7
	global_atomic_add v7, v8, s[4:5]
	v_add_u32_e32 v7, 0x100, v7
	global_atomic_add v7, v8, s[4:5]
	v_add_u32_e32 v7, 0x100, v7
	global_atomic_add v7, v8, s[4:5]
	v_add_u32_e32 v7, 0x100, v7
	global_atomic_add v7, v8, s[4:5]
	v_add_u32_e32 v7, 0x100, v7
	global_atomic_add v7, v8, s[4:5]
	v_add_u32_e32 v7, 0x100, v7
	global_atomic_add v7, v8, s[4:5]
	v_add_u32_e32 v7, 0x100, v7
	global_atomic_add v7, v8, s[4:5]

.LBB0_145:
	s_or_b64 exec, exec, s[2:3]
	s_mov_b32 s2, s91
	s_mov_b32 s4, 0
	s_waitcnt vmcnt(0)
	s_mov_b32 s5, 0
	v_or_b32_e32 v0, s2, v230
	v_cmp_eq_u32_e32 vcc, 0, v0
	s_waitcnt lgkmcnt(0)
	s_barrier
	s_and_saveexec_b64 s[2:3], vcc
	s_cbranch_execz .LBB0_189
	v_writelane_b32 v2, s4, 1
	v_writelane_b32 v2, s5, 2
	v_writelane_b32 v2, s6, 3
	v_writelane_b32 v2, s7, 4
	v_readlane_b32 s4, v251, 0
	v_readlane_b32 s5, v251, 1
	s_getreg_b32 s6, hwreg(HW_REG_XCC_ID, 0, 4)
	s_load_dword s7, s[4:5], 0x100
	s_load_dwordx2 s[4:5], s[4:5], 0xf0
	v_mov_b32_e32 v0, 0x20010
	ds_read_b32 v3, v0
	ds_read_b32 v4, v0 offset:4
	ds_read_b32 v5, v0 offset:8
	s_and_b32 s6, s6, 15
	s_lshl_b32 s6, s6, 8
	v_mov_b32_e32 v8, 1
	v_mov_b32_e32 v14, 0
	s_waitcnt lgkmcnt(0)
	s_add_u32 s4, s4, 0xee42000
	s_addc_u32 s5, s5, 0
	v_mov_b32_e32 v6, s6
	v_add_u32_e32 v7, 0x400, v6
	v_add_u32_e32 v6, 0x1400, v6
	v_add_u32_e32 v13, 0x1000, v6
	buffer_inv sc1
	global_atomic_add v9, v6, v8, s[4:5] sc0
	v_add_u32_e32 v10, 1, v5
	v_mul_lo_u32 v11, v10, v3
	v_mul_lo_u32 v12, v10, v4
	s_waitcnt vmcnt(0)
	v_add_u32_e32 v9, 1, v9
	v_cmp_eq_u32_e32 vcc, v9, v11
	s_cbranch_vccz .Lhb_poll_2
	buffer_wbl2 sc1
	s_waitcnt vmcnt(0)
	v_mov_b32_e32 v7, 0x2400
	global_atomic_add v7, v8, s[4:5]
	v_add_u32_e32 v7, 0x100, v7
	global_atomic_add v7, v8, s[4:5]
	v_add_u32_e32 v7, 0x100, v7
	global_atomic_add v7, v8, s[4:5]
	v_add_u32_e32 v7, 0x100, v7
	global_atomic_add v7, v8, s[4:5]
	v_add_u32_e32 v7, 0x100, v7
	global_atomic_add v7, v8, s[4:5]
	v_add_u32_e32 v7, 0x100, v7
	global_atomic_add v7, v8, s[4:5]
	v_add_u32_e32 v7, 0x100, v7
	global_atomic_add v7, v8, s[4:5]
	v_add_u32_e32 v7, 0x100, v7
	global_atomic_add v7, v8, s[4:5]
	v_add_u32_e32 v7, 0x100, v7
	global_atomic_add v7, v8, s[4:5]
	v_add_u32_e32 v7, 0x100, v7
	global_atomic_add v7, v8, s[4:5]
	v_add_u32_e32 v7, 0x100, v7
	global_atomic_add v7, v8, s[4:5]
	v_add_u32_e32 v7, 0x100, v7
	global_atomic_add v7, v8, s[4:5]
	v_add_u32_e32 v7, 0x100, v7
	global_atomic_add v7, v8, s[4:5]
	v_add_u32_e32 v7, 0x100, v7
	global_atomic_add v7, v8, s[4:5]
	v_add_u32_e32 v7, 0x100, v7
	global_atomic_add v7, v8, s[4:5]
	v_add_u32_e32 v7, 0x100, v7
	global_atomic_add v7, v8, s[4:5]

.LBB0_314:
	s_mov_b32 s0, s91
	s_mov_b32 s64, 0
	s_waitcnt vmcnt(0)
	s_waitcnt vmcnt(0) lgkmcnt(0)
	v_or_b32_e32 v0, s0, v230
	v_cmp_eq_u32_e32 vcc, 0, v0
	s_barrier
	s_and_saveexec_b64 s[0:1], vcc
	s_cbranch_execz .LBB0_358
	v_writelane_b32 v2, s4, 1
	v_writelane_b32 v2, s5, 2
	v_writelane_b32 v2, s6, 3
	v_writelane_b32 v2, s7, 4
	v_readlane_b32 s4, v254, 45
	v_readlane_b32 s5, v254, 46
	s_getreg_b32 s6, hwreg(HW_REG_XCC_ID, 0, 4)
	s_nop 0
	v_mov_b32_e32 v0, 0x20010
	ds_read_b32 v3, v0
	ds_read_b32 v4, v0 offset:4
	ds_read_b32 v5, v0 offset:8
	s_and_b32 s6, s6, 15
	s_lshl_b32 s6, s6, 8
	v_mov_b32_e32 v8, 1
	v_mov_b32_e32 v14, 0
	s_waitcnt lgkmcnt(0)
	s_add_u32 s4, s4, 0xee42000
	s_addc_u32 s5, s5, 0
	v_mov_b32_e32 v6, s6
	v_add_u32_e32 v7, 0x400, v6
	v_add_u32_e32 v6, 0x1400, v6
	v_add_u32_e32 v13, 0x1000, v6
	buffer_inv sc1
	global_atomic_add v9, v6, v8, s[4:5] sc0
	v_add_u32_e32 v10, 1, v5
	v_mul_lo_u32 v11, v10, v3
	v_mul_lo_u32 v12, v10, v4
	s_waitcnt vmcnt(0)
	v_add_u32_e32 v9, 1, v9
	v_cmp_eq_u32_e32 vcc, v9, v11
	s_cbranch_vccz .Lhb_poll_3
	buffer_wbl2 sc1
	s_waitcnt vmcnt(0)
	v_mov_b32_e32 v7, 0x2400
	global_atomic_add v7, v8, s[4:5]
	v_add_u32_e32 v7, 0x100, v7
	global_atomic_add v7, v8, s[4:5]
	v_add_u32_e32 v7, 0x100, v7
	global_atomic_add v7, v8, s[4:5]
	v_add_u32_e32 v7, 0x100, v7
	global_atomic_add v7, v8, s[4:5]
	v_add_u32_e32 v7, 0x100, v7
	global_atomic_add v7, v8, s[4:5]
	v_add_u32_e32 v7, 0x100, v7
	global_atomic_add v7, v8, s[4:5]
	v_add_u32_e32 v7, 0x100, v7
	global_atomic_add v7, v8, s[4:5]
	v_add_u32_e32 v7, 0x100, v7
	global_atomic_add v7, v8, s[4:5]
	v_add_u32_e32 v7, 0x100, v7
	global_atomic_add v7, v8, s[4:5]
	v_add_u32_e32 v7, 0x100, v7
	global_atomic_add v7, v8, s[4:5]
	v_add_u32_e32 v7, 0x100, v7
	global_atomic_add v7, v8, s[4:5]
	v_add_u32_e32 v7, 0x100, v7
	global_atomic_add v7, v8, s[4:5]
	v_add_u32_e32 v7, 0x100, v7
	global_atomic_add v7, v8, s[4:5]
	v_add_u32_e32 v7, 0x100, v7
	global_atomic_add v7, v8, s[4:5]
	v_add_u32_e32 v7, 0x100, v7
	global_atomic_add v7, v8, s[4:5]
	v_add_u32_e32 v7, 0x100, v7
	global_atomic_add v7, v8, s[4:5]

.LBB0_555:
	s_mov_b32 s0, s91
	s_mov_b32 s64, 0
	s_waitcnt vmcnt(0)
	s_waitcnt lgkmcnt(0)
	v_or_b32_e32 v0, s0, v230
	v_cmp_eq_u32_e32 vcc, 0, v0
	s_barrier
	s_and_saveexec_b64 s[0:1], vcc
	s_mov_b32 s70, 0x10000
	s_cbranch_execz .LBB0_599
	v_writelane_b32 v2, s4, 1
	v_writelane_b32 v2, s5, 2
	v_writelane_b32 v2, s6, 3
	v_writelane_b32 v2, s7, 4
	v_readlane_b32 s4, v254, 45
	v_readlane_b32 s5, v254, 46
	s_getreg_b32 s6, hwreg(HW_REG_XCC_ID, 0, 4)
	s_nop 0
	v_mov_b32_e32 v0, 0x20010
	ds_read_b32 v3, v0
	ds_read_b32 v4, v0 offset:4
	ds_read_b32 v5, v0 offset:8
	s_and_b32 s6, s6, 15
	s_lshl_b32 s6, s6, 8
	v_mov_b32_e32 v8, 1
	v_mov_b32_e32 v14, 0
	s_waitcnt lgkmcnt(0)
	s_add_u32 s4, s4, 0xee42000
	s_addc_u32 s5, s5, 0
	v_mov_b32_e32 v6, s6
	v_add_u32_e32 v7, 0x400, v6
	v_add_u32_e32 v6, 0x1400, v6
	v_add_u32_e32 v13, 0x1000, v6
	buffer_inv sc1
	global_atomic_add v9, v6, v8, s[4:5] sc0
	v_add_u32_e32 v10, 1, v5
	v_mul_lo_u32 v11, v10, v3
	v_mul_lo_u32 v12, v10, v4
	s_waitcnt vmcnt(0)
	v_add_u32_e32 v9, 1, v9
	v_cmp_eq_u32_e32 vcc, v9, v11
	s_cbranch_vccz .Lhb_poll_4
	buffer_wbl2 sc1
	s_waitcnt vmcnt(0)
	v_mov_b32_e32 v7, 0x2400
	global_atomic_add v7, v8, s[4:5]
	v_add_u32_e32 v7, 0x100, v7
	global_atomic_add v7, v8, s[4:5]
	v_add_u32_e32 v7, 0x100, v7
	global_atomic_add v7, v8, s[4:5]
	v_add_u32_e32 v7, 0x100, v7
	global_atomic_add v7, v8, s[4:5]
	v_add_u32_e32 v7, 0x100, v7
	global_atomic_add v7, v8, s[4:5]
	v_add_u32_e32 v7, 0x100, v7
	global_atomic_add v7, v8, s[4:5]
	v_add_u32_e32 v7, 0x100, v7
	global_atomic_add v7, v8, s[4:5]
	v_add_u32_e32 v7, 0x100, v7
	global_atomic_add v7, v8, s[4:5]
	v_add_u32_e32 v7, 0x100, v7
	global_atomic_add v7, v8, s[4:5]
	v_add_u32_e32 v7, 0x100, v7
	global_atomic_add v7, v8, s[4:5]
	v_add_u32_e32 v7, 0x100, v7
	global_atomic_add v7, v8, s[4:5]
	v_add_u32_e32 v7, 0x100, v7
	global_atomic_add v7, v8, s[4:5]
	v_add_u32_e32 v7, 0x100, v7
	global_atomic_add v7, v8, s[4:5]
	v_add_u32_e32 v7, 0x100, v7
	global_atomic_add v7, v8, s[4:5]
	v_add_u32_e32 v7, 0x100, v7
	global_atomic_add v7, v8, s[4:5]
	v_add_u32_e32 v7, 0x100, v7
	global_atomic_add v7, v8, s[4:5]

.LBB0_760:
	s_mov_b32 s0, s91
	s_mov_b32 s70, 0
	s_waitcnt vmcnt(0)
	s_waitcnt lgkmcnt(0)
	v_or_b32_e32 v0, s0, v230
	v_cmp_eq_u32_e32 vcc, 0, v0
	s_barrier
	s_and_saveexec_b64 s[0:1], vcc
	s_cbranch_execz .LBB0_804
	v_writelane_b32 v2, s4, 1
	v_writelane_b32 v2, s5, 2
	v_writelane_b32 v2, s6, 3
	v_writelane_b32 v2, s7, 4
	v_readlane_b32 s4, v254, 45
	v_readlane_b32 s5, v254, 46
	s_getreg_b32 s6, hwreg(HW_REG_XCC_ID, 0, 4)
	s_nop 0
	v_mov_b32_e32 v0, 0x20010
	ds_read_b32 v3, v0
	ds_read_b32 v4, v0 offset:4
	ds_read_b32 v5, v0 offset:8
	s_and_b32 s6, s6, 15
	s_lshl_b32 s6, s6, 8
	v_mov_b32_e32 v8, 1
	v_mov_b32_e32 v14, 0
	s_waitcnt lgkmcnt(0)
	s_add_u32 s4, s4, 0xee42000
	s_addc_u32 s5, s5, 0
	v_mov_b32_e32 v6, s6
	v_add_u32_e32 v7, 0x400, v6
	v_add_u32_e32 v6, 0x1400, v6
	v_add_u32_e32 v13, 0x1000, v6
	buffer_inv sc1
	global_atomic_add v9, v6, v8, s[4:5] sc0
	v_add_u32_e32 v10, 1, v5
	v_mul_lo_u32 v11, v10, v3
	v_mul_lo_u32 v12, v10, v4
	s_waitcnt vmcnt(0)
	v_add_u32_e32 v9, 1, v9
	v_cmp_eq_u32_e32 vcc, v9, v11
	s_cbranch_vccz .Lhb_poll_5
	buffer_wbl2 sc1
	s_waitcnt vmcnt(0)
	v_mov_b32_e32 v7, 0x2400
	global_atomic_add v7, v8, s[4:5]
	v_add_u32_e32 v7, 0x100, v7
	global_atomic_add v7, v8, s[4:5]
	v_add_u32_e32 v7, 0x100, v7
	global_atomic_add v7, v8, s[4:5]
	v_add_u32_e32 v7, 0x100, v7
	global_atomic_add v7, v8, s[4:5]
	v_add_u32_e32 v7, 0x100, v7
	global_atomic_add v7, v8, s[4:5]
	v_add_u32_e32 v7, 0x100, v7
	global_atomic_add v7, v8, s[4:5]
	v_add_u32_e32 v7, 0x100, v7
	global_atomic_add v7, v8, s[4:5]
	v_add_u32_e32 v7, 0x100, v7
	global_atomic_add v7, v8, s[4:5]
	v_add_u32_e32 v7, 0x100, v7
	global_atomic_add v7, v8, s[4:5]
	v_add_u32_e32 v7, 0x100, v7
	global_atomic_add v7, v8, s[4:5]
	v_add_u32_e32 v7, 0x100, v7
	global_atomic_add v7, v8, s[4:5]
	v_add_u32_e32 v7, 0x100, v7
	global_atomic_add v7, v8, s[4:5]
	v_add_u32_e32 v7, 0x100, v7
	global_atomic_add v7, v8, s[4:5]
	v_add_u32_e32 v7, 0x100, v7
	global_atomic_add v7, v8, s[4:5]
	v_add_u32_e32 v7, 0x100, v7
	global_atomic_add v7, v8, s[4:5]
	v_add_u32_e32 v7, 0x100, v7
	global_atomic_add v7, v8, s[4:5]

.Lln1_end:
.LBB0_1032:
	v_writelane_b32 v255, s82, 18
	s_nop 1
	v_writelane_b32 v255, s83, 19
	s_mov_b64 s[82:83], 0x20000
	s_or_b64 exec, exec, s[6:7]
	s_mov_b32 s0, s91
	s_mov_b32 s70, 0
	s_waitcnt vmcnt(0)
	s_waitcnt lgkmcnt(0)
	v_or_b32_e32 v0, s0, v230
	v_cmp_eq_u32_e32 vcc, 0, v0
	s_barrier
	s_and_saveexec_b64 s[0:1], vcc
	s_cbranch_execz .LBB0_1076
	v_writelane_b32 v2, s4, 1
	v_writelane_b32 v2, s5, 2
	v_writelane_b32 v2, s6, 3
	v_writelane_b32 v2, s7, 4
	v_readlane_b32 s4, v254, 45
	v_readlane_b32 s5, v254, 46
	s_getreg_b32 s6, hwreg(HW_REG_XCC_ID, 0, 4)
	s_nop 0
	v_mov_b32_e32 v0, 0x20010
	ds_read_b32 v3, v0
	ds_read_b32 v4, v0 offset:4
	ds_read_b32 v5, v0 offset:8
	s_and_b32 s6, s6, 15
	s_lshl_b32 s6, s6, 8
	v_mov_b32_e32 v8, 1
	v_mov_b32_e32 v14, 0
	s_waitcnt lgkmcnt(0)
	s_add_u32 s4, s4, 0xee42000
	s_addc_u32 s5, s5, 0
	v_mov_b32_e32 v6, s6
	v_add_u32_e32 v7, 0x400, v6
	v_add_u32_e32 v6, 0x1400, v6
	v_add_u32_e32 v13, 0x1000, v6
	buffer_inv sc1
	global_atomic_add v9, v6, v8, s[4:5] sc0
	v_add_u32_e32 v10, 1, v5
	v_mul_lo_u32 v11, v10, v3
	v_mul_lo_u32 v12, v10, v4
	s_waitcnt vmcnt(0)
	v_add_u32_e32 v9, 1, v9
	v_cmp_eq_u32_e32 vcc, v9, v11
	s_cbranch_vccz .Lhb_poll_7
	buffer_wbl2 sc1
	s_waitcnt vmcnt(0)
	v_mov_b32_e32 v7, 0x2400
	global_atomic_add v7, v8, s[4:5]
	v_add_u32_e32 v7, 0x100, v7
	global_atomic_add v7, v8, s[4:5]
	v_add_u32_e32 v7, 0x100, v7
	global_atomic_add v7, v8, s[4:5]
	v_add_u32_e32 v7, 0x100, v7
	global_atomic_add v7, v8, s[4:5]
	v_add_u32_e32 v7, 0x100, v7
	global_atomic_add v7, v8, s[4:5]
	v_add_u32_e32 v7, 0x100, v7
	global_atomic_add v7, v8, s[4:5]
	v_add_u32_e32 v7, 0x100, v7
	global_atomic_add v7, v8, s[4:5]
	v_add_u32_e32 v7, 0x100, v7
	global_atomic_add v7, v8, s[4:5]
	v_add_u32_e32 v7, 0x100, v7
	global_atomic_add v7, v8, s[4:5]
	v_add_u32_e32 v7, 0x100, v7
	global_atomic_add v7, v8, s[4:5]
	v_add_u32_e32 v7, 0x100, v7
	global_atomic_add v7, v8, s[4:5]
	v_add_u32_e32 v7, 0x100, v7
	global_atomic_add v7, v8, s[4:5]
	v_add_u32_e32 v7, 0x100, v7
	global_atomic_add v7, v8, s[4:5]
	v_add_u32_e32 v7, 0x100, v7
	global_atomic_add v7, v8, s[4:5]
	v_add_u32_e32 v7, 0x100, v7
	global_atomic_add v7, v8, s[4:5]
	v_add_u32_e32 v7, 0x100, v7
	global_atomic_add v7, v8, s[4:5]

.LBB0_1096:
	s_mov_b32 s0, s91
	s_mov_b32 s36, 0
	s_waitcnt vmcnt(0)
	s_waitcnt vmcnt(0) lgkmcnt(0)
	v_or_b32_e32 v0, s0, v230
	v_cmp_eq_u32_e32 vcc, 0, v0
	s_barrier
	s_and_saveexec_b64 s[0:1], vcc
	s_mov_b32 s70, 0x5a3e000
	s_cbranch_execz .LBB0_1140
	v_writelane_b32 v2, s4, 1
	v_writelane_b32 v2, s5, 2
	v_writelane_b32 v2, s6, 3
	v_writelane_b32 v2, s7, 4
	v_readlane_b32 s4, v254, 45
	v_readlane_b32 s5, v254, 46
	s_getreg_b32 s6, hwreg(HW_REG_XCC_ID, 0, 4)
	s_nop 0
	v_mov_b32_e32 v0, 0x20010
	ds_read_b32 v3, v0
	ds_read_b32 v4, v0 offset:4
	ds_read_b32 v5, v0 offset:8
	s_and_b32 s6, s6, 15
	s_lshl_b32 s6, s6, 8
	v_mov_b32_e32 v8, 1
	v_mov_b32_e32 v14, 0
	s_waitcnt lgkmcnt(0)
	s_add_u32 s4, s4, 0xee42000
	s_addc_u32 s5, s5, 0
	v_mov_b32_e32 v6, s6
	v_add_u32_e32 v7, 0x400, v6
	v_add_u32_e32 v6, 0x1400, v6
	v_add_u32_e32 v13, 0x1000, v6
	buffer_inv sc1
	global_atomic_add v9, v6, v8, s[4:5] sc0
	v_add_u32_e32 v10, 1, v5
	v_mul_lo_u32 v11, v10, v3
	v_mul_lo_u32 v12, v10, v4
	s_waitcnt vmcnt(0)
	v_add_u32_e32 v9, 1, v9
	v_cmp_eq_u32_e32 vcc, v9, v11
	s_cbranch_vccz .Lhb_poll_8
	buffer_wbl2 sc1
	s_waitcnt vmcnt(0)
	v_mov_b32_e32 v7, 0x2400
	global_atomic_add v7, v8, s[4:5]
	v_add_u32_e32 v7, 0x100, v7
	global_atomic_add v7, v8, s[4:5]
	v_add_u32_e32 v7, 0x100, v7
	global_atomic_add v7, v8, s[4:5]
	v_add_u32_e32 v7, 0x100, v7
	global_atomic_add v7, v8, s[4:5]
	v_add_u32_e32 v7, 0x100, v7
	global_atomic_add v7, v8, s[4:5]
	v_add_u32_e32 v7, 0x100, v7
	global_atomic_add v7, v8, s[4:5]
	v_add_u32_e32 v7, 0x100, v7
	global_atomic_add v7, v8, s[4:5]
	v_add_u32_e32 v7, 0x100, v7
	global_atomic_add v7, v8, s[4:5]
	v_add_u32_e32 v7, 0x100, v7
	global_atomic_add v7, v8, s[4:5]
	v_add_u32_e32 v7, 0x100, v7
	global_atomic_add v7, v8, s[4:5]
	v_add_u32_e32 v7, 0x100, v7
	global_atomic_add v7, v8, s[4:5]
	v_add_u32_e32 v7, 0x100, v7
	global_atomic_add v7, v8, s[4:5]
	v_add_u32_e32 v7, 0x100, v7
	global_atomic_add v7, v8, s[4:5]
	v_add_u32_e32 v7, 0x100, v7
	global_atomic_add v7, v8, s[4:5]
	v_add_u32_e32 v7, 0x100, v7
	global_atomic_add v7, v8, s[4:5]
	v_add_u32_e32 v7, 0x100, v7
	global_atomic_add v7, v8, s[4:5]

.LBB0_1146:
	v_mov_b32_e32 v0, v230
	s_mov_b32 s4, s91
	s_mov_b32 s65, s25
	s_mov_b32 s64, 0
	s_xor_b64 s[0:1], s[64:65], s[62:63]
	v_readlane_b32 s5, v253, 29
	s_add_u32 s0, s0, s5
	s_addc_u32 s1, s1, 0
	s_ashr_i32 s5, s4, 2
	s_andn2_b32 s5, s5, 63
	v_and_or_b32 v134, v0, 15, s5
	s_lshr_b32 s4, s4, 1
	v_readlane_b32 s5, v253, 46
	s_and_b32 s4, s4, 0x60
	v_ashrrev_i32_e32 v0, 1, v0
	v_add_u32_e32 v130, s5, v134
	v_readlane_b32 s5, v253, 38
	v_and_b32_e32 v0, -8, v0
	s_add_i32 s4, s4, s5
	v_add_u32_e32 v132, s4, v0
	v_readlane_b32 s4, v253, 40
	v_cvt_pk_bf16_f32 v110, v110, v111
	v_cvt_pk_bf16_f32 v111, v112, v113
	v_cvt_pk_bf16_f32 v112, v106, v107
	v_add_u32_e32 v106, s4, v134
	v_readlane_b32 s4, v253, 41
	v_cvt_pk_bf16_f32 v94, v94, v95
	v_cvt_pk_bf16_f32 v95, v96, v97
	v_cvt_pk_bf16_f32 v96, v90, v91
	v_add_u32_e32 v90, s4, v134
	v_readlane_b32 s4, v253, 42
	v_cvt_pk_bf16_f32 v78, v78, v79
	v_cvt_pk_bf16_f32 v79, v80, v81
	v_cvt_pk_bf16_f32 v80, v74, v75
	v_add_u32_e32 v74, s4, v134
	v_readlane_b32 s4, v253, 43
	v_cvt_pk_bf16_f32 v70, v70, v71
	v_cvt_pk_bf16_f32 v71, v72, v73
	v_cvt_pk_bf16_f32 v72, v66, v67
	v_add_u32_e32 v66, s4, v134
	v_ashrrev_i32_e32 v131, 31, v130
	v_ashrrev_i32_e32 v67, 31, v66
	v_readlane_b32 s4, v253, 44
	v_lshlrev_b64 v[130:131], 11, v[130:131]
	v_ashrrev_i32_e32 v133, 31, v132
	v_lshlrev_b64 v[66:67], 11, v[66:67]
	v_cvt_pk_bf16_f32 v46, v46, v47
	v_cvt_pk_bf16_f32 v47, v48, v49
	v_cvt_pk_bf16_f32 v48, v42, v43
	v_add_u32_e32 v42, s4, v134
	v_lshl_add_u64 v[130:131], s[0:1], 0, v[130:131]
	v_cvt_pk_bf16_f32 v126, v126, v127
	v_cvt_pk_bf16_f32 v127, v128, v129
	v_cvt_pk_bf16_f32 v128, v122, v123
	v_lshlrev_b64 v[122:123], 1, v[132:133]
	v_ashrrev_i32_e32 v107, 31, v106
	v_lshl_add_u64 v[66:67], s[0:1], 0, v[66:67]
	v_ashrrev_i32_e32 v43, 31, v42
	v_readlane_b32 s4, v253, 45
	v_cvt_pk_bf16_f32 v129, v124, v125
	v_lshl_add_u64 v[124:125], v[130:131], 0, v[122:123]
	v_cvt_pk_bf16_f32 v113, v108, v109
	v_lshlrev_b64 v[106:107], 11, v[106:107]
	v_cvt_pk_bf16_f32 v62, v62, v63
	v_cvt_pk_bf16_f32 v63, v64, v65
	v_cvt_pk_bf16_f32 v64, v58, v59
	v_lshl_add_u64 v[58:59], v[66:67], 0, v[122:123]
	v_cvt_pk_bf16_f32 v49, v44, v45
	v_lshlrev_b64 v[42:43], 11, v[42:43]
	v_cvt_pk_bf16_f32 v30, v30, v31
	v_cvt_pk_bf16_f32 v31, v32, v33
	v_cvt_pk_bf16_f32 v32, v26, v27
	v_add_u32_e32 v26, s4, v134
	flat_store_dwordx4 v[124:125], v[110:113] offset:256
	v_ashrrev_i32_e32 v91, 31, v90
	flat_store_dwordx4 v[58:59], v[46:49] offset:256
	v_lshl_add_u64 v[110:111], s[0:1], 0, v[106:107]
	v_ashrrev_i32_e32 v27, 31, v26
	v_lshl_add_u64 v[46:47], s[0:1], 0, v[42:43]
	v_readlane_b32 s4, v253, 47
	v_lshl_add_u64 v[110:111], v[110:111], 0, v[122:123]
	v_cvt_pk_bf16_f32 v97, v92, v93
	v_lshlrev_b64 v[90:91], 11, v[90:91]
	v_lshl_add_u64 v[46:47], v[46:47], 0, v[122:123]
	v_cvt_pk_bf16_f32 v33, v28, v29
	v_lshlrev_b64 v[26:27], 11, v[26:27]
	v_cvt_pk_bf16_f32 v14, v14, v15
	v_cvt_pk_bf16_f32 v15, v16, v17
	v_cvt_pk_bf16_f32 v16, v10, v11
	v_add_u32_e32 v10, s4, v134
	flat_store_dwordx4 v[110:111], v[94:97] offset:256
	v_ashrrev_i32_e32 v75, 31, v74
	flat_store_dwordx4 v[46:47], v[30:33] offset:256
	v_lshl_add_u64 v[94:95], s[0:1], 0, v[90:91]
	v_ashrrev_i32_e32 v11, 31, v10
	v_lshl_add_u64 v[30:31], s[0:1], 0, v[26:27]
	v_lshl_add_u64 v[94:95], v[94:95], 0, v[122:123]
	v_cvt_pk_bf16_f32 v81, v76, v77
	v_lshlrev_b64 v[74:75], 11, v[74:75]
	v_lshl_add_u64 v[30:31], v[30:31], 0, v[122:123]
	v_cvt_pk_bf16_f32 v17, v12, v13
	v_lshlrev_b64 v[10:11], 11, v[10:11]
	flat_store_dwordx4 v[94:95], v[78:81] offset:256
	flat_store_dwordx4 v[30:31], v[14:17] offset:256
	v_cvt_pk_bf16_f32 v106, v118, v119
	v_lshl_add_u64 v[78:79], s[0:1], 0, v[74:75]
	v_lshl_add_u64 v[14:15], s[0:1], 0, v[10:11]
	v_cvt_pk_bf16_f32 v107, v120, v121
	v_cvt_pk_bf16_f32 v108, v114, v115
	v_cvt_pk_bf16_f32 v109, v116, v117
	v_cvt_pk_bf16_f32 v90, v102, v103
	v_cvt_pk_bf16_f32 v91, v104, v105
	v_cvt_pk_bf16_f32 v92, v98, v99
	v_cvt_pk_bf16_f32 v93, v100, v101
	v_cvt_pk_bf16_f32 v74, v86, v87
	v_cvt_pk_bf16_f32 v75, v88, v89
	v_cvt_pk_bf16_f32 v76, v82, v83
	v_cvt_pk_bf16_f32 v77, v84, v85
	v_lshl_add_u64 v[78:79], v[78:79], 0, v[122:123]
	v_cvt_pk_bf16_f32 v73, v68, v69
	v_cvt_pk_bf16_f32 v65, v60, v61
	v_cvt_pk_bf16_f32 v42, v54, v55
	v_cvt_pk_bf16_f32 v43, v56, v57
	v_cvt_pk_bf16_f32 v44, v50, v51
	v_cvt_pk_bf16_f32 v45, v52, v53
	v_cvt_pk_bf16_f32 v26, v38, v39
	v_cvt_pk_bf16_f32 v27, v40, v41
	v_cvt_pk_bf16_f32 v28, v34, v35
	v_cvt_pk_bf16_f32 v29, v36, v37
	v_cvt_pk_bf16_f32 v10, v22, v23
	v_cvt_pk_bf16_f32 v11, v24, v25
	v_cvt_pk_bf16_f32 v12, v18, v19
	v_cvt_pk_bf16_f32 v13, v20, v21
	v_lshl_add_u64 v[14:15], v[14:15], 0, v[122:123]
	v_cvt_pk_bf16_f32 v6, v6, v7
	v_cvt_pk_bf16_f32 v7, v8, v9
	v_cvt_pk_bf16_f32 v8, v2, v3
	v_cvt_pk_bf16_f32 v9, v4, v5
	flat_store_dwordx4 v[124:125], v[126:129]
	flat_store_dwordx4 v[110:111], v[106:109]
	flat_store_dwordx4 v[94:95], v[90:93]
	flat_store_dwordx4 v[78:79], v[74:77]
	flat_store_dwordx4 v[78:79], v[70:73] offset:256
	flat_store_dwordx4 v[58:59], v[62:65]
	flat_store_dwordx4 v[46:47], v[42:45]
	flat_store_dwordx4 v[30:31], v[26:29]
	flat_store_dwordx4 v[14:15], v[10:13]
	flat_store_dwordx4 v[14:15], v[6:9] offset:256
	s_mov_b32 s0, s91
	s_waitcnt vmcnt(0)
	s_barrier
	s_mov_b32 s64, 0
	s_waitcnt vmcnt(0)
	s_waitcnt vmcnt(0) lgkmcnt(0)
	v_or_b32_e32 v0, s0, v230
	v_cmp_eq_u32_e32 vcc, 0, v0
	s_barrier
	s_and_saveexec_b64 s[0:1], vcc
	s_movk_i32 s66, 0x1e00
	s_mov_b32 s67, 0x800000
	s_cbranch_execz .LBB0_1190
	v_writelane_b32 v2, s4, 1
	v_writelane_b32 v2, s5, 2
	v_writelane_b32 v2, s6, 3
	v_writelane_b32 v2, s7, 4
	v_readlane_b32 s4, v254, 45
	v_readlane_b32 s5, v254, 46
	s_getreg_b32 s6, hwreg(HW_REG_XCC_ID, 0, 4)
	s_nop 0
	v_mov_b32_e32 v0, 0x20010
	ds_read_b32 v3, v0
	ds_read_b32 v4, v0 offset:4
	ds_read_b32 v5, v0 offset:8
	s_and_b32 s6, s6, 15
	s_lshl_b32 s6, s6, 8
	v_mov_b32_e32 v8, 1
	v_mov_b32_e32 v14, 0
	s_waitcnt lgkmcnt(0)
	s_add_u32 s4, s4, 0xee42000
	s_addc_u32 s5, s5, 0
	v_mov_b32_e32 v6, s6
	v_add_u32_e32 v7, 0x400, v6
	v_add_u32_e32 v6, 0x1400, v6
	v_add_u32_e32 v13, 0x1000, v6
	buffer_inv sc1
	global_atomic_add v9, v6, v8, s[4:5] sc0
	v_add_u32_e32 v10, 1, v5
	v_mul_lo_u32 v11, v10, v3
	v_mul_lo_u32 v12, v10, v4
	s_waitcnt vmcnt(0)
	v_add_u32_e32 v9, 1, v9
	v_cmp_eq_u32_e32 vcc, v9, v11
	s_cbranch_vccz .Lhb_poll_9
	buffer_wbl2 sc1
	s_waitcnt vmcnt(0)
	v_mov_b32_e32 v7, 0x2400
	global_atomic_add v7, v8, s[4:5]
	v_add_u32_e32 v7, 0x100, v7
	global_atomic_add v7, v8, s[4:5]
	v_add_u32_e32 v7, 0x100, v7
	global_atomic_add v7, v8, s[4:5]
	v_add_u32_e32 v7, 0x100, v7
	global_atomic_add v7, v8, s[4:5]
	v_add_u32_e32 v7, 0x100, v7
	global_atomic_add v7, v8, s[4:5]
	v_add_u32_e32 v7, 0x100, v7
	global_atomic_add v7, v8, s[4:5]
	v_add_u32_e32 v7, 0x100, v7
	global_atomic_add v7, v8, s[4:5]
	v_add_u32_e32 v7, 0x100, v7
	global_atomic_add v7, v8, s[4:5]
	v_add_u32_e32 v7, 0x100, v7
	global_atomic_add v7, v8, s[4:5]
	v_add_u32_e32 v7, 0x100, v7
	global_atomic_add v7, v8, s[4:5]
	v_add_u32_e32 v7, 0x100, v7
	global_atomic_add v7, v8, s[4:5]
	v_add_u32_e32 v7, 0x100, v7
	global_atomic_add v7, v8, s[4:5]
	v_add_u32_e32 v7, 0x100, v7
	global_atomic_add v7, v8, s[4:5]
	v_add_u32_e32 v7, 0x100, v7
	global_atomic_add v7, v8, s[4:5]
	v_add_u32_e32 v7, 0x100, v7
	global_atomic_add v7, v8, s[4:5]
	v_add_u32_e32 v7, 0x100, v7
	global_atomic_add v7, v8, s[4:5]

.LBB0_1212:
	v_writelane_b32 v2, s4, 1
	v_writelane_b32 v2, s5, 2
	v_writelane_b32 v2, s6, 3
	v_writelane_b32 v2, s7, 4
	v_readlane_b32 s4, v254, 45
	v_readlane_b32 s5, v254, 46
	s_getreg_b32 s6, hwreg(HW_REG_XCC_ID, 0, 4)
	s_nop 0
	v_mov_b32_e32 v0, 0x20010
	ds_read_b32 v3, v0
	ds_read_b32 v4, v0 offset:4
	ds_read_b32 v5, v0 offset:8
	s_and_b32 s6, s6, 15
	s_lshl_b32 s6, s6, 8
	v_mov_b32_e32 v8, 1
	v_mov_b32_e32 v14, 0
	s_waitcnt lgkmcnt(0)
	s_add_u32 s4, s4, 0xee42000
	s_addc_u32 s5, s5, 0
	v_mov_b32_e32 v6, s6
	v_add_u32_e32 v7, 0x400, v6
	v_add_u32_e32 v6, 0x1400, v6
	v_add_u32_e32 v13, 0x1000, v6
	buffer_inv sc1
	global_atomic_add v9, v6, v8, s[4:5] sc0
	v_add_u32_e32 v10, 1, v5
	v_mul_lo_u32 v11, v10, v3
	v_mul_lo_u32 v12, v10, v4
	s_waitcnt vmcnt(0)
	v_add_u32_e32 v9, 1, v9
	v_cmp_eq_u32_e32 vcc, v9, v11
	s_cbranch_vccz .Lhb_poll_10
	buffer_wbl2 sc1
	s_waitcnt vmcnt(0)
	v_mov_b32_e32 v7, 0x2400
	global_atomic_add v7, v8, s[4:5]
	v_add_u32_e32 v7, 0x100, v7
	global_atomic_add v7, v8, s[4:5]
	v_add_u32_e32 v7, 0x100, v7
	global_atomic_add v7, v8, s[4:5]
	v_add_u32_e32 v7, 0x100, v7
	global_atomic_add v7, v8, s[4:5]
	v_add_u32_e32 v7, 0x100, v7
	global_atomic_add v7, v8, s[4:5]
	v_add_u32_e32 v7, 0x100, v7
	global_atomic_add v7, v8, s[4:5]
	v_add_u32_e32 v7, 0x100, v7
	global_atomic_add v7, v8, s[4:5]
	v_add_u32_e32 v7, 0x100, v7
	global_atomic_add v7, v8, s[4:5]
	v_add_u32_e32 v7, 0x100, v7
	global_atomic_add v7, v8, s[4:5]
	v_add_u32_e32 v7, 0x100, v7
	global_atomic_add v7, v8, s[4:5]
	v_add_u32_e32 v7, 0x100, v7
	global_atomic_add v7, v8, s[4:5]
	v_add_u32_e32 v7, 0x100, v7
	global_atomic_add v7, v8, s[4:5]
	v_add_u32_e32 v7, 0x100, v7
	global_atomic_add v7, v8, s[4:5]
	v_add_u32_e32 v7, 0x100, v7
	global_atomic_add v7, v8, s[4:5]
	v_add_u32_e32 v7, 0x100, v7
	global_atomic_add v7, v8, s[4:5]
	v_add_u32_e32 v7, 0x100, v7
	global_atomic_add v7, v8, s[4:5]
